# grid barrier: L1 invalidate (buffer_inv sc1) issued at arrival by wave 1 instead of after the release is observed
# speedup vs baseline: 1.0121x; 1.0121x over previous
.LBB0_21:
	s_andn2_b64 vcc, exec, s[4:5]
	s_cbranch_vccnz .LBB0_15
	s_cmp_le_i32 s11, s78
	s_cbranch_scc1 .LBB0_76
	s_waitcnt vmcnt(0)
	s_barrier
	v_readfirstlane_b32 s100, v0
	s_lshr_b32 s100, s100, 6
	s_cmp_lg_u32 s100, 1
	s_cbranch_scc1 .Lbar_noinv
	buffer_inv sc1
	s_waitcnt vmcnt(0)
.Lbar_noinv:
	s_and_saveexec_b64 s[4:5], s[72:73]
	s_cbranch_execz .LBB0_75
	v_readlane_b32 s6, v254, 20
	s_waitcnt vmcnt(0) expcnt(0) lgkmcnt(0)
	s_nop 0
	v_mov_b32_e32 v1, s6
	ds_read_b32 v4, v1
	v_readlane_b32 s6, v254, 21
	s_waitcnt lgkmcnt(0)
	v_cmp_ne_u32_e32 vcc, 0, v4
	v_mov_b32_e32 v1, s6
	ds_read_b32 v1, v1
	s_cbranch_vccnz .LBB0_39
	v_readlane_b32 s12, v252, 2
	v_readlane_b32 s13, v252, 3
	s_load_dwordx2 s[6:7], s[12:13], 0x4
	s_mov_b32 s17, 1
	s_waitcnt lgkmcnt(0)
	s_mul_i32 s16, s6, s83
	s_mul_i32 s16, s16, s7
	s_branch .LBB0_27

.LBB0_54:
	s_or_b64 exec, exec, s[12:13]
	s_waitcnt vmcnt(0)
.LBB0_55:
	s_andn2_saveexec_b64 s[6:7], s[6:7]
	s_cbranch_execz .LBB0_75
	s_mov_b64 s[6:7], exec
	buffer_wbl2 sc1
	s_waitcnt lgkmcnt(0)
	s_waitcnt vmcnt(0)
	v_mbcnt_lo_u32_b32 v2, s6, 0
	v_mbcnt_hi_u32_b32 v2, s7, v2
	v_cmp_eq_u32_e32 vcc, 0, v2
	s_and_saveexec_b64 s[12:13], vcc
	s_cbranch_execz .LBB0_58
	s_bcnt1_i32_b64 s6, s[6:7]
	v_mov_b32_e32 v4, s6
	v_readlane_b32 s6, v253, 0
	v_readlane_b32 s7, v253, 1
	s_nop 4
	global_atomic_add v4, v3, v4, s[6:7] sc0

.LBB0_72:
	s_or_b64 exec, exec, s[6:7]
	s_mov_b64 s[6:7], exec
	v_mbcnt_lo_u32_b32 v1, s6, 0
	v_mbcnt_hi_u32_b32 v1, s7, v1
	v_cmp_eq_u32_e32 vcc, 0, v1
	s_waitcnt vmcnt(0)
	s_and_saveexec_b64 s[12:13], vcc
	s_cbranch_execz .LBB0_74
	s_bcnt1_i32_b64 s6, s[6:7]
	v_mov_b32_e32 v1, s6
	v_readlane_b32 s6, v252, 62
	v_readlane_b32 s7, v252, 63
	s_nop 4
	global_atomic_add v3, v1, s[6:7]
